# GU1/GU2 SwiGLU epilogue stores lane-permuted (quad-row-contiguous) like the split-K epilogues
# speedup vs baseline: 1.0435x; 1.0031x over previous
.LBB0_397:
	v_mul_f32_e32 v158, 0xbfb8aa3b, v124
	v_mul_f32_e32 v159, 0xbfb8aa3b, v125
	v_exp_f32_e32 v158, v158
	v_exp_f32_e32 v159, v159
	v_mul_f32_e32 v160, 0xbfb8aa3b, v126
	v_mul_f32_e32 v161, 0xbfb8aa3b, v127
	v_exp_f32_e32 v160, v160
	v_exp_f32_e32 v161, v161
	v_add_f32_e32 v158, 1.0, v158
	v_add_f32_e32 v159, 1.0, v159
	v_rcp_f32_e32 v158, v158
	v_rcp_f32_e32 v159, v159
	v_add_f32_e32 v160, 1.0, v160
	v_add_f32_e32 v161, 1.0, v161
	v_rcp_f32_e32 v160, v160
	v_rcp_f32_e32 v161, v161
	v_pk_mul_f32 v[124:125], v[124:125], v[158:159]
	v_lshl_add_u32 v155, s54, 8, v129
	v_pk_mul_f32 v[120:121], v[124:125], v[120:121]
	v_pk_mul_f32 v[124:125], v[126:127], v[160:161]
	v_cvt_pk_bf16_f32 v120, v120, v121
	v_mul_f32_e32 v121, 0xbfb8aa3b, v116
	v_pk_mul_f32 v[122:123], v[124:125], v[122:123]
	v_exp_f32_e32 v124, v121
	v_mul_f32_e32 v121, 0xbfb8aa3b, v117
	v_exp_f32_e32 v125, v121
	v_cvt_pk_bf16_f32 v121, v122, v123
	v_add_f32_e32 v122, 1.0, v124
	v_mul_f32_e32 v124, 0xbfb8aa3b, v118
	v_add_f32_e32 v123, 1.0, v125
	v_mul_f32_e32 v125, 0xbfb8aa3b, v119
	v_exp_f32_e32 v124, v124
	v_exp_f32_e32 v125, v125
	v_rcp_f32_e32 v122, v122
	v_rcp_f32_e32 v123, v123
	v_add_f32_e32 v124, 1.0, v124
	v_add_f32_e32 v125, 1.0, v125
	v_rcp_f32_e32 v124, v124
	v_rcp_f32_e32 v125, v125
	v_pk_mul_f32 v[116:117], v[116:117], v[122:123]
	v_lshl_or_b32 v146, s52, 7, v151
	v_pk_mul_f32 v[112:113], v[116:117], v[112:113]
	v_mul_f32_e32 v116, 0xbfb8aa3b, v110
	v_cvt_pk_bf16_f32 v122, v112, v113
	v_pk_mul_f32 v[112:113], v[118:119], v[124:125]
	v_mul_f32_e32 v117, 0xbfb8aa3b, v111
	v_pk_mul_f32 v[112:113], v[112:113], v[114:115]
	v_mul_f32_e32 v114, 0xbfb8aa3b, v108
	v_mul_f32_e32 v115, 0xbfb8aa3b, v109
	v_exp_f32_e32 v114, v114
	v_exp_f32_e32 v115, v115
	v_exp_f32_e32 v116, v116
	v_exp_f32_e32 v117, v117
	v_add_f32_e32 v114, 1.0, v114
	v_add_f32_e32 v115, 1.0, v115
	v_rcp_f32_e32 v114, v114
	v_rcp_f32_e32 v115, v115
	v_add_f32_e32 v116, 1.0, v116
	v_add_f32_e32 v117, 1.0, v117
	v_rcp_f32_e32 v116, v116
	v_rcp_f32_e32 v117, v117
	v_pk_mul_f32 v[108:109], v[108:109], v[114:115]
	v_ashrrev_i32_e32 v147, 31, v146
	v_pk_mul_f32 v[104:105], v[108:109], v[104:105]
	v_pk_mul_f32 v[108:109], v[110:111], v[116:117]
	v_cvt_pk_bf16_f32 v104, v104, v105
	v_mul_f32_e32 v105, 0xbfb8aa3b, v100
	v_pk_mul_f32 v[106:107], v[108:109], v[106:107]
	v_exp_f32_e32 v108, v105
	v_mul_f32_e32 v105, 0xbfb8aa3b, v101
	v_exp_f32_e32 v109, v105
	v_cvt_pk_bf16_f32 v105, v106, v107
	v_add_f32_e32 v106, 1.0, v108
	v_mul_f32_e32 v108, 0xbfb8aa3b, v102
	v_add_f32_e32 v107, 1.0, v109
	v_mul_f32_e32 v109, 0xbfb8aa3b, v103
	v_exp_f32_e32 v108, v108
	v_exp_f32_e32 v109, v109
	v_rcp_f32_e32 v106, v106
	v_rcp_f32_e32 v107, v107
	v_add_f32_e32 v108, 1.0, v108
	v_add_f32_e32 v109, 1.0, v109
	v_rcp_f32_e32 v108, v108
	v_rcp_f32_e32 v109, v109
	v_pk_mul_f32 v[100:101], v[100:101], v[106:107]
	v_mov_b64_e32 v[148:149], s[6:7]
	v_pk_mul_f32 v[96:97], v[100:101], v[96:97]
	v_mul_f32_e32 v100, 0xbfb8aa3b, v94
	v_cvt_pk_bf16_f32 v106, v96, v97
	v_pk_mul_f32 v[96:97], v[102:103], v[108:109]
	v_mul_f32_e32 v101, 0xbfb8aa3b, v95
	v_pk_mul_f32 v[96:97], v[96:97], v[98:99]
	v_mul_f32_e32 v98, 0xbfb8aa3b, v92
	v_mul_f32_e32 v99, 0xbfb8aa3b, v93
	v_exp_f32_e32 v98, v98
	v_exp_f32_e32 v99, v99
	v_exp_f32_e32 v100, v100
	v_exp_f32_e32 v101, v101
	v_add_f32_e32 v98, 1.0, v98
	v_add_f32_e32 v99, 1.0, v99
	v_rcp_f32_e32 v98, v98
	v_rcp_f32_e32 v99, v99
	v_add_f32_e32 v100, 1.0, v100
	v_add_f32_e32 v101, 1.0, v101
	v_rcp_f32_e32 v100, v100
	v_rcp_f32_e32 v101, v101
	v_pk_mul_f32 v[92:93], v[92:93], v[98:99]
	v_cvt_pk_bf16_f32 v123, v112, v113
	v_pk_mul_f32 v[88:89], v[92:93], v[88:89]
	v_pk_mul_f32 v[92:93], v[94:95], v[100:101]
	v_cvt_pk_bf16_f32 v88, v88, v89
	v_mul_f32_e32 v89, 0xbfb8aa3b, v84
	v_pk_mul_f32 v[90:91], v[92:93], v[90:91]
	v_exp_f32_e32 v92, v89
	v_mul_f32_e32 v89, 0xbfb8aa3b, v85
	v_exp_f32_e32 v93, v89
	v_cvt_pk_bf16_f32 v89, v90, v91
	v_add_f32_e32 v90, 1.0, v92
	v_mul_f32_e32 v92, 0xbfb8aa3b, v86
	v_add_f32_e32 v91, 1.0, v93
	v_mul_f32_e32 v93, 0xbfb8aa3b, v87
	v_exp_f32_e32 v92, v92
	v_exp_f32_e32 v93, v93
	v_rcp_f32_e32 v90, v90
	v_rcp_f32_e32 v91, v91
	v_add_f32_e32 v92, 1.0, v92
	v_add_f32_e32 v93, 1.0, v93
	v_rcp_f32_e32 v92, v92
	v_rcp_f32_e32 v93, v93
	v_pk_mul_f32 v[84:85], v[84:85], v[90:91]
	v_or_b32_e32 v112, 16, v155
	v_pk_mul_f32 v[80:81], v[84:85], v[80:81]
	v_mul_f32_e32 v84, 0xbfb8aa3b, v78
	v_cvt_pk_bf16_f32 v90, v80, v81
	v_pk_mul_f32 v[80:81], v[86:87], v[92:93]
	v_mul_f32_e32 v85, 0xbfb8aa3b, v79
	v_pk_mul_f32 v[80:81], v[80:81], v[82:83]
	v_mul_f32_e32 v82, 0xbfb8aa3b, v76
	v_mul_f32_e32 v83, 0xbfb8aa3b, v77
	v_exp_f32_e32 v82, v82
	v_exp_f32_e32 v83, v83
	v_exp_f32_e32 v84, v84
	v_exp_f32_e32 v85, v85
	v_add_f32_e32 v82, 1.0, v82
	v_add_f32_e32 v83, 1.0, v83
	v_rcp_f32_e32 v82, v82
	v_rcp_f32_e32 v83, v83
	v_add_f32_e32 v84, 1.0, v84
	v_add_f32_e32 v85, 1.0, v85
	v_rcp_f32_e32 v84, v84
	v_rcp_f32_e32 v85, v85
	v_pk_mul_f32 v[76:77], v[76:77], v[82:83]
	v_cvt_pk_bf16_f32 v107, v96, v97
	v_pk_mul_f32 v[72:73], v[76:77], v[72:73]
	v_pk_mul_f32 v[76:77], v[78:79], v[84:85]
	v_cvt_pk_bf16_f32 v72, v72, v73
	v_mul_f32_e32 v73, 0xbfb8aa3b, v68
	v_pk_mul_f32 v[74:75], v[76:77], v[74:75]
	v_exp_f32_e32 v76, v73
	v_mul_f32_e32 v73, 0xbfb8aa3b, v69
	v_exp_f32_e32 v77, v73
	v_cvt_pk_bf16_f32 v73, v74, v75
	v_add_f32_e32 v74, 1.0, v76
	v_mul_f32_e32 v76, 0xbfb8aa3b, v70
	v_add_f32_e32 v75, 1.0, v77
	v_mul_f32_e32 v77, 0xbfb8aa3b, v71
	v_exp_f32_e32 v76, v76
	v_exp_f32_e32 v77, v77
	v_rcp_f32_e32 v74, v74
	v_rcp_f32_e32 v75, v75
	v_add_f32_e32 v76, 1.0, v76
	v_add_f32_e32 v77, 1.0, v77
	v_rcp_f32_e32 v76, v76
	v_rcp_f32_e32 v77, v77
	v_pk_mul_f32 v[68:69], v[68:69], v[74:75]
	v_or_b32_e32 v96, 32, v155
	v_pk_mul_f32 v[64:65], v[68:69], v[64:65]
	v_mul_f32_e32 v68, 0xbfb8aa3b, v62
	v_cvt_pk_bf16_f32 v74, v64, v65
	v_pk_mul_f32 v[64:65], v[70:71], v[76:77]
	v_mul_f32_e32 v69, 0xbfb8aa3b, v63
	v_pk_mul_f32 v[64:65], v[64:65], v[66:67]
	v_mul_f32_e32 v66, 0xbfb8aa3b, v60
	v_mul_f32_e32 v67, 0xbfb8aa3b, v61
	v_exp_f32_e32 v66, v66
	v_exp_f32_e32 v67, v67
	v_exp_f32_e32 v68, v68
	v_exp_f32_e32 v69, v69
	v_add_f32_e32 v66, 1.0, v66
	v_add_f32_e32 v67, 1.0, v67
	v_rcp_f32_e32 v66, v66
	v_rcp_f32_e32 v67, v67
	v_add_f32_e32 v68, 1.0, v68
	v_add_f32_e32 v69, 1.0, v69
	v_rcp_f32_e32 v68, v68
	v_rcp_f32_e32 v69, v69
	v_pk_mul_f32 v[60:61], v[60:61], v[66:67]
	v_cvt_pk_bf16_f32 v91, v80, v81
	v_pk_mul_f32 v[56:57], v[60:61], v[56:57]
	v_pk_mul_f32 v[60:61], v[62:63], v[68:69]
	v_cvt_pk_bf16_f32 v56, v56, v57
	v_mul_f32_e32 v57, 0xbfb8aa3b, v52
	v_pk_mul_f32 v[58:59], v[60:61], v[58:59]
	v_exp_f32_e32 v60, v57
	v_mul_f32_e32 v57, 0xbfb8aa3b, v53
	v_exp_f32_e32 v61, v57
	v_cvt_pk_bf16_f32 v57, v58, v59
	v_add_f32_e32 v58, 1.0, v60
	v_mul_f32_e32 v60, 0xbfb8aa3b, v54
	v_add_f32_e32 v59, 1.0, v61
	v_mul_f32_e32 v61, 0xbfb8aa3b, v55
	v_exp_f32_e32 v60, v60
	v_exp_f32_e32 v61, v61
	v_rcp_f32_e32 v58, v58
	v_rcp_f32_e32 v59, v59
	v_add_f32_e32 v60, 1.0, v60
	v_add_f32_e32 v61, 1.0, v61
	v_rcp_f32_e32 v60, v60
	v_rcp_f32_e32 v61, v61
	v_pk_mul_f32 v[52:53], v[52:53], v[58:59]
	v_or_b32_e32 v80, 48, v155
	v_pk_mul_f32 v[48:49], v[52:53], v[48:49]
	v_mul_f32_e32 v52, 0xbfb8aa3b, v46
	v_cvt_pk_bf16_f32 v58, v48, v49
	v_pk_mul_f32 v[48:49], v[54:55], v[60:61]
	v_mul_f32_e32 v53, 0xbfb8aa3b, v47
	v_pk_mul_f32 v[48:49], v[48:49], v[50:51]
	v_mul_f32_e32 v50, 0xbfb8aa3b, v44
	v_mul_f32_e32 v51, 0xbfb8aa3b, v45
	v_exp_f32_e32 v50, v50
	v_exp_f32_e32 v51, v51
	v_exp_f32_e32 v52, v52
	v_exp_f32_e32 v53, v53
	v_add_f32_e32 v50, 1.0, v50
	v_add_f32_e32 v51, 1.0, v51
	v_rcp_f32_e32 v50, v50
	v_rcp_f32_e32 v51, v51
	v_add_f32_e32 v52, 1.0, v52
	v_add_f32_e32 v53, 1.0, v53
	v_rcp_f32_e32 v52, v52
	v_rcp_f32_e32 v53, v53
	v_pk_mul_f32 v[44:45], v[44:45], v[50:51]
	v_cvt_pk_bf16_f32 v75, v64, v65
	v_pk_mul_f32 v[40:41], v[44:45], v[40:41]
	v_pk_mul_f32 v[44:45], v[46:47], v[52:53]
	v_cvt_pk_bf16_f32 v40, v40, v41
	v_mul_f32_e32 v41, 0xbfb8aa3b, v36
	v_pk_mul_f32 v[42:43], v[44:45], v[42:43]
	v_exp_f32_e32 v44, v41
	v_mul_f32_e32 v41, 0xbfb8aa3b, v37
	v_exp_f32_e32 v45, v41
	v_cvt_pk_bf16_f32 v41, v42, v43
	v_add_f32_e32 v42, 1.0, v44
	v_mul_f32_e32 v44, 0xbfb8aa3b, v38
	v_add_f32_e32 v43, 1.0, v45
	v_mul_f32_e32 v45, 0xbfb8aa3b, v39
	v_exp_f32_e32 v44, v44
	v_exp_f32_e32 v45, v45
	v_rcp_f32_e32 v42, v42
	v_rcp_f32_e32 v43, v43
	v_add_f32_e32 v44, 1.0, v44
	v_add_f32_e32 v45, 1.0, v45
	v_rcp_f32_e32 v44, v44
	v_rcp_f32_e32 v45, v45
	v_pk_mul_f32 v[36:37], v[36:37], v[42:43]
	v_add_u32_e32 v64, 0x80, v155
	v_pk_mul_f32 v[32:33], v[36:37], v[32:33]
	v_mul_f32_e32 v36, 0xbfb8aa3b, v30
	v_cvt_pk_bf16_f32 v42, v32, v33
	v_pk_mul_f32 v[32:33], v[38:39], v[44:45]
	v_mul_f32_e32 v37, 0xbfb8aa3b, v31
	v_pk_mul_f32 v[32:33], v[32:33], v[34:35]
	v_mul_f32_e32 v34, 0xbfb8aa3b, v28
	v_mul_f32_e32 v35, 0xbfb8aa3b, v29
	v_exp_f32_e32 v34, v34
	v_exp_f32_e32 v35, v35
	v_exp_f32_e32 v36, v36
	v_exp_f32_e32 v37, v37
	v_add_f32_e32 v34, 1.0, v34
	v_add_f32_e32 v35, 1.0, v35
	v_rcp_f32_e32 v34, v34
	v_rcp_f32_e32 v35, v35
	v_add_f32_e32 v36, 1.0, v36
	v_add_f32_e32 v37, 1.0, v37
	v_rcp_f32_e32 v36, v36
	v_rcp_f32_e32 v37, v37
	v_pk_mul_f32 v[28:29], v[28:29], v[34:35]
	v_cvt_pk_bf16_f32 v59, v48, v49
	v_pk_mul_f32 v[24:25], v[28:29], v[24:25]
	v_pk_mul_f32 v[28:29], v[30:31], v[36:37]
	v_cvt_pk_bf16_f32 v24, v24, v25
	v_mul_f32_e32 v25, 0xbfb8aa3b, v20
	v_pk_mul_f32 v[26:27], v[28:29], v[26:27]
	v_exp_f32_e32 v28, v25
	v_mul_f32_e32 v25, 0xbfb8aa3b, v21
	v_exp_f32_e32 v29, v25
	v_cvt_pk_bf16_f32 v25, v26, v27
	v_add_f32_e32 v26, 1.0, v28
	v_mul_f32_e32 v28, 0xbfb8aa3b, v22
	v_add_f32_e32 v27, 1.0, v29
	v_mul_f32_e32 v29, 0xbfb8aa3b, v23
	v_exp_f32_e32 v28, v28
	v_exp_f32_e32 v29, v29
	v_rcp_f32_e32 v26, v26
	v_rcp_f32_e32 v27, v27
	v_add_f32_e32 v28, 1.0, v28
	v_add_f32_e32 v29, 1.0, v29
	v_rcp_f32_e32 v28, v28
	v_rcp_f32_e32 v29, v29
	v_pk_mul_f32 v[20:21], v[20:21], v[26:27]
	v_add_u32_e32 v48, 0x90, v155
	v_pk_mul_f32 v[16:17], v[20:21], v[16:17]
	v_mul_f32_e32 v20, 0xbfb8aa3b, v14
	v_cvt_pk_bf16_f32 v26, v16, v17
	v_pk_mul_f32 v[16:17], v[22:23], v[28:29]
	v_mul_f32_e32 v21, 0xbfb8aa3b, v15
	v_pk_mul_f32 v[16:17], v[16:17], v[18:19]
	v_mul_f32_e32 v18, 0xbfb8aa3b, v12
	v_mul_f32_e32 v19, 0xbfb8aa3b, v13
	v_exp_f32_e32 v18, v18
	v_exp_f32_e32 v19, v19
	v_exp_f32_e32 v20, v20
	v_exp_f32_e32 v21, v21
	v_add_f32_e32 v18, 1.0, v18
	v_add_f32_e32 v19, 1.0, v19
	v_rcp_f32_e32 v18, v18
	v_rcp_f32_e32 v19, v19
	v_add_f32_e32 v20, 1.0, v20
	v_add_f32_e32 v21, 1.0, v21
	v_rcp_f32_e32 v20, v20
	v_rcp_f32_e32 v21, v21
	v_pk_mul_f32 v[12:13], v[12:13], v[18:19]
	v_cvt_pk_bf16_f32 v43, v32, v33
	v_pk_mul_f32 v[8:9], v[12:13], v[8:9]
	v_pk_mul_f32 v[12:13], v[14:15], v[20:21]
	v_cvt_pk_bf16_f32 v8, v8, v9
	v_mul_f32_e32 v9, 0xbfb8aa3b, v4
	v_pk_mul_f32 v[10:11], v[12:13], v[10:11]
	v_exp_f32_e32 v12, v9
	v_mul_f32_e32 v9, 0xbfb8aa3b, v5
	v_exp_f32_e32 v13, v9
	v_cvt_pk_bf16_f32 v9, v10, v11
	v_add_f32_e32 v10, 1.0, v12
	v_mul_f32_e32 v12, 0xbfb8aa3b, v6
	v_add_f32_e32 v11, 1.0, v13
	v_mul_f32_e32 v13, 0xbfb8aa3b, v7
	v_exp_f32_e32 v12, v12
	v_exp_f32_e32 v13, v13
	v_rcp_f32_e32 v10, v10
	v_rcp_f32_e32 v11, v11
	v_add_f32_e32 v12, 1.0, v12
	v_add_f32_e32 v13, 1.0, v13
	v_rcp_f32_e32 v12, v12
	v_rcp_f32_e32 v13, v13
	v_pk_mul_f32 v[4:5], v[4:5], v[10:11]
	v_add_u32_e32 v32, 0xa0, v155
	v_pk_mul_f32 v[0:1], v[4:5], v[0:1]
	v_cvt_pk_bf16_f32 v27, v16, v17
	v_add_u32_e32 v16, 0xb0, v155
	v_cvt_pk_bf16_f32 v10, v0, v1
	v_pk_mul_f32 v[0:1], v[6:7], v[12:13]
	v_mad_i64_i32 v[156:157], s[56:57], v155, s76, v[148:149]
	v_lshlrev_b64 v[146:147], 1, v[146:147]
	v_mad_i64_i32 v[112:113], s[56:57], v112, s76, v[148:149]
	v_mad_i64_i32 v[96:97], s[56:57], v96, s76, v[148:149]
	v_mad_i64_i32 v[80:81], s[56:57], v80, s76, v[148:149]
	v_mad_i64_i32 v[64:65], s[56:57], v64, s76, v[148:149]
	v_mad_i64_i32 v[48:49], s[56:57], v48, s76, v[148:149]
	v_mad_i64_i32 v[32:33], s[56:57], v32, s76, v[148:149]
	v_mad_i64_i32 v[16:17], s[56:57], v16, s76, v[148:149]
	v_pk_mul_f32 v[0:1], v[0:1], v[2:3]
	v_lshl_add_u64 v[156:157], v[156:157], 0, v[146:147]
	v_lshl_add_u64 v[112:113], v[112:113], 0, v[146:147]
	v_lshl_add_u64 v[96:97], v[96:97], 0, v[146:147]
	v_lshl_add_u64 v[80:81], v[80:81], 0, v[146:147]
	v_lshl_add_u64 v[64:65], v[64:65], 0, v[146:147]
	v_lshl_add_u64 v[48:49], v[48:49], 0, v[146:147]
	v_lshl_add_u64 v[32:33], v[32:33], 0, v[146:147]
	v_lshl_add_u64 v[16:17], v[16:17], 0, v[146:147]
	v_cvt_pk_bf16_f32 v11, v0, v1
	s_andn2_b64 vcc, exec, s[4:5]
	s_mov_b64 s[4:5], -1
	global_store_dwordx4 v[156:157], v[120:123], off
	v_and_b32_e32 v254, 63, v128
	v_and_b32_e32 v255, 3, v254
	v_lshrrev_b32_e32 v254, 2, v254
	v_lshl_or_b32 v254, v255, 4, v254
	v_lshlrev_b32_e32 v254, 2, v254
	ds_bpermute_b32 v238, v254, v104
	ds_bpermute_b32 v239, v254, v105
	ds_bpermute_b32 v240, v254, v106
	ds_bpermute_b32 v241, v254, v107
	ds_bpermute_b32 v236, v254, v112
	ds_bpermute_b32 v237, v254, v113
	ds_bpermute_b32 v244, v254, v88
	ds_bpermute_b32 v245, v254, v89
	ds_bpermute_b32 v246, v254, v90
	ds_bpermute_b32 v247, v254, v91
	ds_bpermute_b32 v242, v254, v96
	ds_bpermute_b32 v243, v254, v97
	ds_bpermute_b32 v250, v254, v72
	ds_bpermute_b32 v251, v254, v73
	ds_bpermute_b32 v252, v254, v74
	ds_bpermute_b32 v253, v254, v75
	ds_bpermute_b32 v248, v254, v80
	ds_bpermute_b32 v249, v254, v81
	s_waitcnt lgkmcnt(12)
	global_store_dwordx4 v[236:237], v[238:241], off
	s_nop 0
	ds_bpermute_b32 v238, v254, v56
	ds_bpermute_b32 v239, v254, v57
	ds_bpermute_b32 v240, v254, v58
	ds_bpermute_b32 v241, v254, v59
	ds_bpermute_b32 v236, v254, v64
	ds_bpermute_b32 v237, v254, v65
	s_waitcnt lgkmcnt(12)
	global_store_dwordx4 v[242:243], v[244:247], off
	s_nop 0
	ds_bpermute_b32 v244, v254, v40
	ds_bpermute_b32 v245, v254, v41
	ds_bpermute_b32 v246, v254, v42
	ds_bpermute_b32 v247, v254, v43
	ds_bpermute_b32 v242, v254, v48
	ds_bpermute_b32 v243, v254, v49
	s_waitcnt lgkmcnt(12)
	global_store_dwordx4 v[248:249], v[250:253], off
	s_nop 0
	ds_bpermute_b32 v250, v254, v24
	ds_bpermute_b32 v251, v254, v25
	ds_bpermute_b32 v252, v254, v26
	ds_bpermute_b32 v253, v254, v27
	ds_bpermute_b32 v248, v254, v32
	ds_bpermute_b32 v249, v254, v33
	s_waitcnt lgkmcnt(12)
	global_store_dwordx4 v[236:237], v[238:241], off
	s_nop 0
	ds_bpermute_b32 v238, v254, v8
	ds_bpermute_b32 v239, v254, v9
	ds_bpermute_b32 v240, v254, v10
	ds_bpermute_b32 v241, v254, v11
	ds_bpermute_b32 v236, v254, v16
	ds_bpermute_b32 v237, v254, v17
	s_waitcnt lgkmcnt(12)
	global_store_dwordx4 v[242:243], v[244:247], off
	s_waitcnt lgkmcnt(6)
	global_store_dwordx4 v[248:249], v[250:253], off
	s_waitcnt lgkmcnt(0)
	global_store_dwordx4 v[236:237], v[238:241], off
	s_cbranch_vccnz .LBB0_390
	s_andn2_b64 vcc, exec, s[0:1]
	s_cbranch_vccnz .LBB0_389
	s_barrier
	s_branch .LBB0_389

.LBB0_1694:
	v_mul_f32_e32 v158, 0xbfb8aa3b, v124
	v_mul_f32_e32 v159, 0xbfb8aa3b, v125
	v_exp_f32_e32 v158, v158
	v_exp_f32_e32 v159, v159
	v_mul_f32_e32 v160, 0xbfb8aa3b, v126
	v_mul_f32_e32 v161, 0xbfb8aa3b, v127
	v_exp_f32_e32 v160, v160
	v_exp_f32_e32 v161, v161
	v_add_f32_e32 v158, 1.0, v158
	v_add_f32_e32 v159, 1.0, v159
	v_rcp_f32_e32 v158, v158
	v_rcp_f32_e32 v159, v159
	v_add_f32_e32 v160, 1.0, v160
	v_add_f32_e32 v161, 1.0, v161
	v_rcp_f32_e32 v160, v160
	v_rcp_f32_e32 v161, v161
	v_pk_mul_f32 v[124:125], v[124:125], v[158:159]
	v_lshl_add_u32 v155, s24, 8, v129
	v_pk_mul_f32 v[120:121], v[124:125], v[120:121]
	v_pk_mul_f32 v[124:125], v[126:127], v[160:161]
	v_cvt_pk_bf16_f32 v120, v120, v121
	v_mul_f32_e32 v121, 0xbfb8aa3b, v116
	v_pk_mul_f32 v[122:123], v[124:125], v[122:123]
	v_exp_f32_e32 v124, v121
	v_mul_f32_e32 v121, 0xbfb8aa3b, v117
	v_exp_f32_e32 v125, v121
	v_cvt_pk_bf16_f32 v121, v122, v123
	v_add_f32_e32 v122, 1.0, v124
	v_mul_f32_e32 v124, 0xbfb8aa3b, v118
	v_add_f32_e32 v123, 1.0, v125
	v_mul_f32_e32 v125, 0xbfb8aa3b, v119
	v_exp_f32_e32 v124, v124
	v_exp_f32_e32 v125, v125
	v_rcp_f32_e32 v122, v122
	v_rcp_f32_e32 v123, v123
	v_add_f32_e32 v124, 1.0, v124
	v_add_f32_e32 v125, 1.0, v125
	v_rcp_f32_e32 v124, v124
	v_rcp_f32_e32 v125, v125
	v_pk_mul_f32 v[116:117], v[116:117], v[122:123]
	v_lshl_or_b32 v146, s22, 7, v151
	v_pk_mul_f32 v[112:113], v[116:117], v[112:113]
	v_mul_f32_e32 v116, 0xbfb8aa3b, v110
	v_cvt_pk_bf16_f32 v122, v112, v113
	v_pk_mul_f32 v[112:113], v[118:119], v[124:125]
	v_mul_f32_e32 v117, 0xbfb8aa3b, v111
	v_pk_mul_f32 v[112:113], v[112:113], v[114:115]
	v_mul_f32_e32 v114, 0xbfb8aa3b, v108
	v_mul_f32_e32 v115, 0xbfb8aa3b, v109
	v_exp_f32_e32 v114, v114
	v_exp_f32_e32 v115, v115
	v_exp_f32_e32 v116, v116
	v_exp_f32_e32 v117, v117
	v_add_f32_e32 v114, 1.0, v114
	v_add_f32_e32 v115, 1.0, v115
	v_rcp_f32_e32 v114, v114
	v_rcp_f32_e32 v115, v115
	v_add_f32_e32 v116, 1.0, v116
	v_add_f32_e32 v117, 1.0, v117
	v_rcp_f32_e32 v116, v116
	v_rcp_f32_e32 v117, v117
	v_pk_mul_f32 v[108:109], v[108:109], v[114:115]
	v_ashrrev_i32_e32 v147, 31, v146
	v_pk_mul_f32 v[104:105], v[108:109], v[104:105]
	v_pk_mul_f32 v[108:109], v[110:111], v[116:117]
	v_cvt_pk_bf16_f32 v104, v104, v105
	v_mul_f32_e32 v105, 0xbfb8aa3b, v100
	v_pk_mul_f32 v[106:107], v[108:109], v[106:107]
	v_exp_f32_e32 v108, v105
	v_mul_f32_e32 v105, 0xbfb8aa3b, v101
	v_exp_f32_e32 v109, v105
	v_cvt_pk_bf16_f32 v105, v106, v107
	v_add_f32_e32 v106, 1.0, v108
	v_mul_f32_e32 v108, 0xbfb8aa3b, v102
	v_add_f32_e32 v107, 1.0, v109
	v_mul_f32_e32 v109, 0xbfb8aa3b, v103
	v_exp_f32_e32 v108, v108
	v_exp_f32_e32 v109, v109
	v_rcp_f32_e32 v106, v106
	v_rcp_f32_e32 v107, v107
	v_add_f32_e32 v108, 1.0, v108
	v_add_f32_e32 v109, 1.0, v109
	v_rcp_f32_e32 v108, v108
	v_rcp_f32_e32 v109, v109
	v_pk_mul_f32 v[100:101], v[100:101], v[106:107]
	v_mov_b64_e32 v[148:149], s[6:7]
	v_pk_mul_f32 v[96:97], v[100:101], v[96:97]
	v_mul_f32_e32 v100, 0xbfb8aa3b, v94
	v_cvt_pk_bf16_f32 v106, v96, v97
	v_pk_mul_f32 v[96:97], v[102:103], v[108:109]
	v_mul_f32_e32 v101, 0xbfb8aa3b, v95
	v_pk_mul_f32 v[96:97], v[96:97], v[98:99]
	v_mul_f32_e32 v98, 0xbfb8aa3b, v92
	v_mul_f32_e32 v99, 0xbfb8aa3b, v93
	v_exp_f32_e32 v98, v98
	v_exp_f32_e32 v99, v99
	v_exp_f32_e32 v100, v100
	v_exp_f32_e32 v101, v101
	v_add_f32_e32 v98, 1.0, v98
	v_add_f32_e32 v99, 1.0, v99
	v_rcp_f32_e32 v98, v98
	v_rcp_f32_e32 v99, v99
	v_add_f32_e32 v100, 1.0, v100
	v_add_f32_e32 v101, 1.0, v101
	v_rcp_f32_e32 v100, v100
	v_rcp_f32_e32 v101, v101
	v_pk_mul_f32 v[92:93], v[92:93], v[98:99]
	v_cvt_pk_bf16_f32 v123, v112, v113
	v_pk_mul_f32 v[88:89], v[92:93], v[88:89]
	v_pk_mul_f32 v[92:93], v[94:95], v[100:101]
	v_cvt_pk_bf16_f32 v88, v88, v89
	v_mul_f32_e32 v89, 0xbfb8aa3b, v84
	v_pk_mul_f32 v[90:91], v[92:93], v[90:91]
	v_exp_f32_e32 v92, v89
	v_mul_f32_e32 v89, 0xbfb8aa3b, v85
	v_exp_f32_e32 v93, v89
	v_cvt_pk_bf16_f32 v89, v90, v91
	v_add_f32_e32 v90, 1.0, v92
	v_mul_f32_e32 v92, 0xbfb8aa3b, v86
	v_add_f32_e32 v91, 1.0, v93
	v_mul_f32_e32 v93, 0xbfb8aa3b, v87
	v_exp_f32_e32 v92, v92
	v_exp_f32_e32 v93, v93
	v_rcp_f32_e32 v90, v90
	v_rcp_f32_e32 v91, v91
	v_add_f32_e32 v92, 1.0, v92
	v_add_f32_e32 v93, 1.0, v93
	v_rcp_f32_e32 v92, v92
	v_rcp_f32_e32 v93, v93
	v_pk_mul_f32 v[84:85], v[84:85], v[90:91]
	v_or_b32_e32 v112, 16, v155
	v_pk_mul_f32 v[80:81], v[84:85], v[80:81]
	v_mul_f32_e32 v84, 0xbfb8aa3b, v78
	v_cvt_pk_bf16_f32 v90, v80, v81
	v_pk_mul_f32 v[80:81], v[86:87], v[92:93]
	v_mul_f32_e32 v85, 0xbfb8aa3b, v79
	v_pk_mul_f32 v[80:81], v[80:81], v[82:83]
	v_mul_f32_e32 v82, 0xbfb8aa3b, v76
	v_mul_f32_e32 v83, 0xbfb8aa3b, v77
	v_exp_f32_e32 v82, v82
	v_exp_f32_e32 v83, v83
	v_exp_f32_e32 v84, v84
	v_exp_f32_e32 v85, v85
	v_add_f32_e32 v82, 1.0, v82
	v_add_f32_e32 v83, 1.0, v83
	v_rcp_f32_e32 v82, v82
	v_rcp_f32_e32 v83, v83
	v_add_f32_e32 v84, 1.0, v84
	v_add_f32_e32 v85, 1.0, v85
	v_rcp_f32_e32 v84, v84
	v_rcp_f32_e32 v85, v85
	v_pk_mul_f32 v[76:77], v[76:77], v[82:83]
	v_cvt_pk_bf16_f32 v107, v96, v97
	v_pk_mul_f32 v[72:73], v[76:77], v[72:73]
	v_pk_mul_f32 v[76:77], v[78:79], v[84:85]
	v_cvt_pk_bf16_f32 v72, v72, v73
	v_mul_f32_e32 v73, 0xbfb8aa3b, v68
	v_pk_mul_f32 v[74:75], v[76:77], v[74:75]
	v_exp_f32_e32 v76, v73
	v_mul_f32_e32 v73, 0xbfb8aa3b, v69
	v_exp_f32_e32 v77, v73
	v_cvt_pk_bf16_f32 v73, v74, v75
	v_add_f32_e32 v74, 1.0, v76
	v_mul_f32_e32 v76, 0xbfb8aa3b, v70
	v_add_f32_e32 v75, 1.0, v77
	v_mul_f32_e32 v77, 0xbfb8aa3b, v71
	v_exp_f32_e32 v76, v76
	v_exp_f32_e32 v77, v77
	v_rcp_f32_e32 v74, v74
	v_rcp_f32_e32 v75, v75
	v_add_f32_e32 v76, 1.0, v76
	v_add_f32_e32 v77, 1.0, v77
	v_rcp_f32_e32 v76, v76
	v_rcp_f32_e32 v77, v77
	v_pk_mul_f32 v[68:69], v[68:69], v[74:75]
	v_or_b32_e32 v96, 32, v155
	v_pk_mul_f32 v[64:65], v[68:69], v[64:65]
	v_mul_f32_e32 v68, 0xbfb8aa3b, v62
	v_cvt_pk_bf16_f32 v74, v64, v65
	v_pk_mul_f32 v[64:65], v[70:71], v[76:77]
	v_mul_f32_e32 v69, 0xbfb8aa3b, v63
	v_pk_mul_f32 v[64:65], v[64:65], v[66:67]
	v_mul_f32_e32 v66, 0xbfb8aa3b, v60
	v_mul_f32_e32 v67, 0xbfb8aa3b, v61
	v_exp_f32_e32 v66, v66
	v_exp_f32_e32 v67, v67
	v_exp_f32_e32 v68, v68
	v_exp_f32_e32 v69, v69
	v_add_f32_e32 v66, 1.0, v66
	v_add_f32_e32 v67, 1.0, v67
	v_rcp_f32_e32 v66, v66
	v_rcp_f32_e32 v67, v67
	v_add_f32_e32 v68, 1.0, v68
	v_add_f32_e32 v69, 1.0, v69
	v_rcp_f32_e32 v68, v68
	v_rcp_f32_e32 v69, v69
	v_pk_mul_f32 v[60:61], v[60:61], v[66:67]
	v_cvt_pk_bf16_f32 v91, v80, v81
	v_pk_mul_f32 v[56:57], v[60:61], v[56:57]
	v_pk_mul_f32 v[60:61], v[62:63], v[68:69]
	v_cvt_pk_bf16_f32 v56, v56, v57
	v_mul_f32_e32 v57, 0xbfb8aa3b, v52
	v_pk_mul_f32 v[58:59], v[60:61], v[58:59]
	v_exp_f32_e32 v60, v57
	v_mul_f32_e32 v57, 0xbfb8aa3b, v53
	v_exp_f32_e32 v61, v57
	v_cvt_pk_bf16_f32 v57, v58, v59
	v_add_f32_e32 v58, 1.0, v60
	v_mul_f32_e32 v60, 0xbfb8aa3b, v54
	v_add_f32_e32 v59, 1.0, v61
	v_mul_f32_e32 v61, 0xbfb8aa3b, v55
	v_exp_f32_e32 v60, v60
	v_exp_f32_e32 v61, v61
	v_rcp_f32_e32 v58, v58
	v_rcp_f32_e32 v59, v59
	v_add_f32_e32 v60, 1.0, v60
	v_add_f32_e32 v61, 1.0, v61
	v_rcp_f32_e32 v60, v60
	v_rcp_f32_e32 v61, v61
	v_pk_mul_f32 v[52:53], v[52:53], v[58:59]
	v_or_b32_e32 v80, 48, v155
	v_pk_mul_f32 v[48:49], v[52:53], v[48:49]
	v_mul_f32_e32 v52, 0xbfb8aa3b, v46
	v_cvt_pk_bf16_f32 v58, v48, v49
	v_pk_mul_f32 v[48:49], v[54:55], v[60:61]
	v_mul_f32_e32 v53, 0xbfb8aa3b, v47
	v_pk_mul_f32 v[48:49], v[48:49], v[50:51]
	v_mul_f32_e32 v50, 0xbfb8aa3b, v44
	v_mul_f32_e32 v51, 0xbfb8aa3b, v45
	v_exp_f32_e32 v50, v50
	v_exp_f32_e32 v51, v51
	v_exp_f32_e32 v52, v52
	v_exp_f32_e32 v53, v53
	v_add_f32_e32 v50, 1.0, v50
	v_add_f32_e32 v51, 1.0, v51
	v_rcp_f32_e32 v50, v50
	v_rcp_f32_e32 v51, v51
	v_add_f32_e32 v52, 1.0, v52
	v_add_f32_e32 v53, 1.0, v53
	v_rcp_f32_e32 v52, v52
	v_rcp_f32_e32 v53, v53
	v_pk_mul_f32 v[44:45], v[44:45], v[50:51]
	v_cvt_pk_bf16_f32 v75, v64, v65
	v_pk_mul_f32 v[40:41], v[44:45], v[40:41]
	v_pk_mul_f32 v[44:45], v[46:47], v[52:53]
	v_cvt_pk_bf16_f32 v40, v40, v41
	v_mul_f32_e32 v41, 0xbfb8aa3b, v36
	v_pk_mul_f32 v[42:43], v[44:45], v[42:43]
	v_exp_f32_e32 v44, v41
	v_mul_f32_e32 v41, 0xbfb8aa3b, v37
	v_exp_f32_e32 v45, v41
	v_cvt_pk_bf16_f32 v41, v42, v43
	v_add_f32_e32 v42, 1.0, v44
	v_mul_f32_e32 v44, 0xbfb8aa3b, v38
	v_add_f32_e32 v43, 1.0, v45
	v_mul_f32_e32 v45, 0xbfb8aa3b, v39
	v_exp_f32_e32 v44, v44
	v_exp_f32_e32 v45, v45
	v_rcp_f32_e32 v42, v42
	v_rcp_f32_e32 v43, v43
	v_add_f32_e32 v44, 1.0, v44
	v_add_f32_e32 v45, 1.0, v45
	v_rcp_f32_e32 v44, v44
	v_rcp_f32_e32 v45, v45
	v_pk_mul_f32 v[36:37], v[36:37], v[42:43]
	v_add_u32_e32 v64, 0x80, v155
	v_pk_mul_f32 v[32:33], v[36:37], v[32:33]
	v_mul_f32_e32 v36, 0xbfb8aa3b, v30
	v_cvt_pk_bf16_f32 v42, v32, v33
	v_pk_mul_f32 v[32:33], v[38:39], v[44:45]
	v_mul_f32_e32 v37, 0xbfb8aa3b, v31
	v_pk_mul_f32 v[32:33], v[32:33], v[34:35]
	v_mul_f32_e32 v34, 0xbfb8aa3b, v28
	v_mul_f32_e32 v35, 0xbfb8aa3b, v29
	v_exp_f32_e32 v34, v34
	v_exp_f32_e32 v35, v35
	v_exp_f32_e32 v36, v36
	v_exp_f32_e32 v37, v37
	v_add_f32_e32 v34, 1.0, v34
	v_add_f32_e32 v35, 1.0, v35
	v_rcp_f32_e32 v34, v34
	v_rcp_f32_e32 v35, v35
	v_add_f32_e32 v36, 1.0, v36
	v_add_f32_e32 v37, 1.0, v37
	v_rcp_f32_e32 v36, v36
	v_rcp_f32_e32 v37, v37
	v_pk_mul_f32 v[28:29], v[28:29], v[34:35]
	v_cvt_pk_bf16_f32 v59, v48, v49
	v_pk_mul_f32 v[24:25], v[28:29], v[24:25]
	v_pk_mul_f32 v[28:29], v[30:31], v[36:37]
	v_cvt_pk_bf16_f32 v24, v24, v25
	v_mul_f32_e32 v25, 0xbfb8aa3b, v20
	v_pk_mul_f32 v[26:27], v[28:29], v[26:27]
	v_exp_f32_e32 v28, v25
	v_mul_f32_e32 v25, 0xbfb8aa3b, v21
	v_exp_f32_e32 v29, v25
	v_cvt_pk_bf16_f32 v25, v26, v27
	v_add_f32_e32 v26, 1.0, v28
	v_mul_f32_e32 v28, 0xbfb8aa3b, v22
	v_add_f32_e32 v27, 1.0, v29
	v_mul_f32_e32 v29, 0xbfb8aa3b, v23
	v_exp_f32_e32 v28, v28
	v_exp_f32_e32 v29, v29
	v_rcp_f32_e32 v26, v26
	v_rcp_f32_e32 v27, v27
	v_add_f32_e32 v28, 1.0, v28
	v_add_f32_e32 v29, 1.0, v29
	v_rcp_f32_e32 v28, v28
	v_rcp_f32_e32 v29, v29
	v_pk_mul_f32 v[20:21], v[20:21], v[26:27]
	v_add_u32_e32 v48, 0x90, v155
	v_pk_mul_f32 v[16:17], v[20:21], v[16:17]
	v_mul_f32_e32 v20, 0xbfb8aa3b, v14
	v_cvt_pk_bf16_f32 v26, v16, v17
	v_pk_mul_f32 v[16:17], v[22:23], v[28:29]
	v_mul_f32_e32 v21, 0xbfb8aa3b, v15
	v_pk_mul_f32 v[16:17], v[16:17], v[18:19]
	v_mul_f32_e32 v18, 0xbfb8aa3b, v12
	v_mul_f32_e32 v19, 0xbfb8aa3b, v13
	v_exp_f32_e32 v18, v18
	v_exp_f32_e32 v19, v19
	v_exp_f32_e32 v20, v20
	v_exp_f32_e32 v21, v21
	v_add_f32_e32 v18, 1.0, v18
	v_add_f32_e32 v19, 1.0, v19
	v_rcp_f32_e32 v18, v18
	v_rcp_f32_e32 v19, v19
	v_add_f32_e32 v20, 1.0, v20
	v_add_f32_e32 v21, 1.0, v21
	v_rcp_f32_e32 v20, v20
	v_rcp_f32_e32 v21, v21
	v_pk_mul_f32 v[12:13], v[12:13], v[18:19]
	v_cvt_pk_bf16_f32 v43, v32, v33
	v_pk_mul_f32 v[8:9], v[12:13], v[8:9]
	v_pk_mul_f32 v[12:13], v[14:15], v[20:21]
	v_cvt_pk_bf16_f32 v8, v8, v9
	v_mul_f32_e32 v9, 0xbfb8aa3b, v4
	v_pk_mul_f32 v[10:11], v[12:13], v[10:11]
	v_exp_f32_e32 v12, v9
	v_mul_f32_e32 v9, 0xbfb8aa3b, v5
	v_exp_f32_e32 v13, v9
	v_cvt_pk_bf16_f32 v9, v10, v11
	v_add_f32_e32 v10, 1.0, v12
	v_mul_f32_e32 v12, 0xbfb8aa3b, v6
	v_add_f32_e32 v11, 1.0, v13
	v_mul_f32_e32 v13, 0xbfb8aa3b, v7
	v_exp_f32_e32 v12, v12
	v_exp_f32_e32 v13, v13
	v_rcp_f32_e32 v10, v10
	v_rcp_f32_e32 v11, v11
	v_add_f32_e32 v12, 1.0, v12
	v_add_f32_e32 v13, 1.0, v13
	v_rcp_f32_e32 v12, v12
	v_rcp_f32_e32 v13, v13
	v_pk_mul_f32 v[4:5], v[4:5], v[10:11]
	v_add_u32_e32 v32, 0xa0, v155
	v_pk_mul_f32 v[0:1], v[4:5], v[0:1]
	v_cvt_pk_bf16_f32 v27, v16, v17
	v_add_u32_e32 v16, 0xb0, v155
	v_cvt_pk_bf16_f32 v10, v0, v1
	v_pk_mul_f32 v[0:1], v[6:7], v[12:13]
	v_mad_i64_i32 v[156:157], s[26:27], v155, s54, v[148:149]
	v_lshlrev_b64 v[146:147], 1, v[146:147]
	v_mad_i64_i32 v[112:113], s[26:27], v112, s54, v[148:149]
	v_mad_i64_i32 v[96:97], s[26:27], v96, s54, v[148:149]
	v_mad_i64_i32 v[80:81], s[26:27], v80, s54, v[148:149]
	v_mad_i64_i32 v[64:65], s[26:27], v64, s54, v[148:149]
	v_mad_i64_i32 v[48:49], s[26:27], v48, s54, v[148:149]
	v_mad_i64_i32 v[32:33], s[26:27], v32, s54, v[148:149]
	v_mad_i64_i32 v[16:17], s[26:27], v16, s54, v[148:149]
	v_pk_mul_f32 v[0:1], v[0:1], v[2:3]
	v_lshl_add_u64 v[156:157], v[156:157], 0, v[146:147]
	v_lshl_add_u64 v[112:113], v[112:113], 0, v[146:147]
	v_lshl_add_u64 v[96:97], v[96:97], 0, v[146:147]
	v_lshl_add_u64 v[80:81], v[80:81], 0, v[146:147]
	v_lshl_add_u64 v[64:65], v[64:65], 0, v[146:147]
	v_lshl_add_u64 v[48:49], v[48:49], 0, v[146:147]
	v_lshl_add_u64 v[32:33], v[32:33], 0, v[146:147]
	v_lshl_add_u64 v[16:17], v[16:17], 0, v[146:147]
	v_cvt_pk_bf16_f32 v11, v0, v1
	s_andn2_b64 vcc, exec, s[4:5]
	s_mov_b64 s[4:5], -1
	global_store_dwordx4 v[156:157], v[120:123], off
	v_and_b32_e32 v254, 63, v128
	v_and_b32_e32 v255, 3, v254
	v_lshrrev_b32_e32 v254, 2, v254
	v_lshl_or_b32 v254, v255, 4, v254
	v_lshlrev_b32_e32 v254, 2, v254
	ds_bpermute_b32 v238, v254, v104
	ds_bpermute_b32 v239, v254, v105
	ds_bpermute_b32 v240, v254, v106
	ds_bpermute_b32 v241, v254, v107
	ds_bpermute_b32 v236, v254, v112
	ds_bpermute_b32 v237, v254, v113
	ds_bpermute_b32 v244, v254, v88
	ds_bpermute_b32 v245, v254, v89
	ds_bpermute_b32 v246, v254, v90
	ds_bpermute_b32 v247, v254, v91
	ds_bpermute_b32 v242, v254, v96
	ds_bpermute_b32 v243, v254, v97
	ds_bpermute_b32 v250, v254, v72
	ds_bpermute_b32 v251, v254, v73
	ds_bpermute_b32 v252, v254, v74
	ds_bpermute_b32 v253, v254, v75
	ds_bpermute_b32 v248, v254, v80
	ds_bpermute_b32 v249, v254, v81
	s_waitcnt lgkmcnt(12)
	global_store_dwordx4 v[236:237], v[238:241], off
	s_nop 0
	ds_bpermute_b32 v238, v254, v56
	ds_bpermute_b32 v239, v254, v57
	ds_bpermute_b32 v240, v254, v58
	ds_bpermute_b32 v241, v254, v59
	ds_bpermute_b32 v236, v254, v64
	ds_bpermute_b32 v237, v254, v65
	s_waitcnt lgkmcnt(12)
	global_store_dwordx4 v[242:243], v[244:247], off
	s_nop 0
	ds_bpermute_b32 v244, v254, v40
	ds_bpermute_b32 v245, v254, v41
	ds_bpermute_b32 v246, v254, v42
	ds_bpermute_b32 v247, v254, v43
	ds_bpermute_b32 v242, v254, v48
	ds_bpermute_b32 v243, v254, v49
	s_waitcnt lgkmcnt(12)
	global_store_dwordx4 v[248:249], v[250:253], off
	s_nop 0
	ds_bpermute_b32 v250, v254, v24
	ds_bpermute_b32 v251, v254, v25
	ds_bpermute_b32 v252, v254, v26
	ds_bpermute_b32 v253, v254, v27
	ds_bpermute_b32 v248, v254, v32
	ds_bpermute_b32 v249, v254, v33
	s_waitcnt lgkmcnt(12)
	global_store_dwordx4 v[236:237], v[238:241], off
	s_nop 0
	ds_bpermute_b32 v238, v254, v8
	ds_bpermute_b32 v239, v254, v9
	ds_bpermute_b32 v240, v254, v10
	ds_bpermute_b32 v241, v254, v11
	ds_bpermute_b32 v236, v254, v16
	ds_bpermute_b32 v237, v254, v17
	s_waitcnt lgkmcnt(12)
	global_store_dwordx4 v[242:243], v[244:247], off
	s_waitcnt lgkmcnt(6)
	global_store_dwordx4 v[248:249], v[250:253], off
	s_waitcnt lgkmcnt(0)
	global_store_dwordx4 v[236:237], v[238:241], off
	s_cbranch_vccnz .LBB0_1687
	s_andn2_b64 vcc, exec, s[2:3]
	s_cbranch_vccnz .LBB0_1686
	s_barrier
	s_branch .LBB0_1686
